# in-proj A parks 8 stores per wave (rg4-rg7): K-loop glds addresses recomputed from SGPR bases to free v244-251; two trickle slots per iteration from iteration 2
# baseline (speedup 1.0000x reference)
;     ...
;         const bool has_next = S.next(ui + 1, nxt);
;         const char* nA = has_next ? (const char*)g.A + (size_t)nxt.pm * tstep : cA; const char* nB = has_next ? (const char*)g.Bt + (size_t)nxt.pn * tstep : cB;
;         for (int t = 0; t < nt; t += 2) {
.LBB0_205:
	s_ashr_i32 s31, s30, 31
	s_lshl_b64 s[48:49], s[30:31], 19
	s_add_u32 s48, s16, s48
	s_addc_u32 s49, s17, s49
	s_and_b64 s[60:61], s[36:37], exec
	s_cselect_b32 s2, s49, s39
	s_cselect_b32 s31, s48, s38
	s_ashr_i32 s29, s28, 31
	s_lshl_b64 s[60:61], s[28:29], 19
	v_readlane_b32 s76, v253, 18
	v_readlane_b32 s77, v253, 19
	s_add_u32 s78, s76, s60
	s_addc_u32 s79, s77, s61
	s_and_b64 s[60:61], s[36:37], exec
	s_cselect_b32 s29, s79, s73
	s_cselect_b32 s60, s78, s72
	s_add_u32 s38, s38, 0x40080
	s_addc_u32 s39, s39, 0
	s_add_u32 s61, s72, 0x100
	s_addc_u32 s80, s73, 0
	s_mov_b32 s81, -2
	s_cmp_eq_u32 s101, 8
	s_cbranch_scc0 .Lpka_nomove
	v_mov_b32_e32 v162, v214
	v_mov_b32_e32 v163, v215
	v_mov_b32_e32 v164, v216
	v_mov_b32_e32 v165, v217
	v_mov_b32_e32 v190, v218
	v_mov_b32_e32 v191, v219
	v_mov_b32_e32 v192, v220
	v_mov_b32_e32 v193, v221

; #define PG8_STAGE(bufoff, gbase, voff) do { _Pragma("unroll") for (int _i = 0; _i < 2; ++_i) \
;         __builtin_amdgcn_global_load_lds((const unsigned*)((const char*)(gbase) + (voff)[_i]), (PG8_LAS unsigned*)(lds + (bufoff) + ldsw + _i * 8192), 16, 0, 0); } while (0)
; #define PG8_LDA(dst, b, h) do { _Pragma("unroll") for (int m = 0; m < 4; ++m) _Pragma("unroll") for (int k = 0; k < 2; ++k) dst[m][k] = *(const PG8_LAS bf16x8*)(lds + PG8_SA(b, h) + aoff + m * 2048 + k * 1024); } while (0)
; #define PG8_LDB(dst, b, h) do { _Pragma("unroll") for (int n = 0; n < 2; ++n) _Pragma("unroll") for (int k = 0; k < 2; ++k) dst[n][k] = *(const PG8_LAS bf16x8*)(lds + PG8_SB(b, h) + boff + n * 2048 + k * 1024); } while (0)
; #define PG8_SCHED __builtin_amdgcn_sched_barrier(0)
;     ...
;         for (int t = 0; t < nt; t += 2) {
;             const bool last = (t == nt - 2);
;             const char* a1 = cA + (size_t)(t + 1) * kstep;
;             const char* a2 = last ? nA : cA + (size_t)(t + 2) * kstep; const char* b2 = last ? nB : cB + (size_t)(t + 2) * kstep;
;             const char* a3 = a2 + kstep; const char* b3 = b2 + kstep;
;             PG8_LDB(B0, 0, 0); PG8_LDB(B1, 0, 1); PG8_SCHED; PG8_LDA(At, 0, 0); PG8_STAGE(PG8_SA(1, 1), a1 + hstep, voffA);
.LBB0_206:
	s_add_u32 s72, s38, 0xfffc0080
	s_addc_u32 s73, s39, -1
	s_add_i32 s82, 0, 0x10000
	s_cmp_eq_u32 s81, 12
	s_cselect_b32 s77, s2, s73
	s_cselect_b32 s76, s31, s72
	s_cselect_b32 s73, s29, s80
	s_cselect_b32 s72, s60, s61
	s_add_i32 s86, 0, 0x14000
	s_waitcnt lgkmcnt(0)
	v_add_u32_e32 v156, s82, v195
	v_add_u32_e32 v183, s86, v195
	ds_read_b128 v[144:147], v156
	ds_read_b128 v[148:151], v156 offset:1024
	ds_read_b128 v[152:155], v156 offset:2048
	ds_read_b128 v[156:159], v156 offset:3072
	ds_read_b128 v[186:189], v183
	ds_read_b128 v[198:201], v183 offset:1024
	ds_read_b128 v[202:205], v183 offset:2048
	ds_read_b128 v[206:209], v183 offset:3072
	v_lshl_add_u64 v[242:243], s[38:39], 0, v[178:179]
	s_add_i32 m0, s63, 0xc000
	ds_read_b128 v[210:213], v197
	ds_read_b128 v[214:217], v197 offset:1024
	ds_read_b128 v[218:221], v197 offset:2048
	ds_read_b128 v[222:225], v197 offset:3072
	ds_read_b128 v[226:229], v197 offset:4096
	ds_read_b128 v[230:233], v197 offset:5120
	ds_read_b128 v[234:237], v197 offset:6144
	ds_read_b128 v[238:241], v197 offset:7168
	global_load_lds_dwordx4 v[242:243], off
	v_lshl_add_u64 v[242:243], s[38:39], 0, v[180:181]
	s_add_i32 m0, s63, 0xe000
	s_nop 0
	global_load_lds_dwordx4 v[242:243], off
	s_lshl_b32 s100, s100, 1
	s_and_b32 s100, s100, 6
	s_cmp_eq_u32 s101, 0
	s_cbranch_scc1 .Lpka_na
	s_cmp_lt_i32 s81, 2
	s_cbranch_scc1 .Lpka_na
	s_or_b32 s100, s100, 1
	s_cmp_eq_u32 s101, 8
	s_cbranch_scc1 .Lpka_s0a
	s_cmp_eq_u32 s101, 7
	s_cbranch_scc1 .Lpka_s1a
	s_cmp_eq_u32 s101, 6
	s_cbranch_scc1 .Lpka_s2a
	s_cmp_eq_u32 s101, 5
	s_cbranch_scc1 .Lpka_s3a
	s_cmp_eq_u32 s101, 4
	s_cbranch_scc1 .Lpka_s4a
	s_cmp_eq_u32 s101, 3
	s_cbranch_scc1 .Lpka_s5a
	s_cmp_eq_u32 s101, 2
	s_cbranch_scc1 .Lpka_s6a
	global_store_dwordx4 v[254:255], v[12:15], off offset:64
	s_branch .Lpka_ia
.Lpka_s0a:
	global_store_dwordx4 v[254:255], v[244:247], off
	s_branch .Lpka_ia
.Lpka_s1a:
	global_store_dwordx4 v[254:255], v[248:251], off offset:64
	v_add_co_u32_e32 v254, vcc, s88, v254
	s_nop 1
	v_addc_co_u32_e32 v255, vcc, 0, v255, vcc
	s_branch .Lpka_ia

; #define PG8_STAGE(bufoff, gbase, voff) do { _Pragma("unroll") for (int _i = 0; _i < 2; ++_i) \
;         __builtin_amdgcn_global_load_lds((const unsigned*)((const char*)(gbase) + (voff)[_i]), (PG8_LAS unsigned*)(lds + (bufoff) + ldsw + _i * 8192), 16, 0, 0); } while (0)
; #define PG8_LDA(dst, b, h) do { _Pragma("unroll") for (int m = 0; m < 4; ++m) _Pragma("unroll") for (int k = 0; k < 2; ++k) dst[m][k] = *(const PG8_LAS bf16x8*)(lds + PG8_SA(b, h) + aoff + m * 2048 + k * 1024); } while (0)
; #define PG8_WAIT_V(n) asm volatile("s_waitcnt vmcnt(" #n ")" ::: "memory")
; #define PG8_WAIT_L(n) asm volatile("s_waitcnt lgkmcnt(" #n ")" ::: "memory")
; #define PG8_BAR __builtin_amdgcn_s_barrier()
; #define PG8_SCHED __builtin_amdgcn_sched_barrier(0)
;     ...
;             PG8_WAIT_V(8); PG8_WAIT_L(0); PG8_BAR; PG8_MMA(0, 0, At, B0); PG8_MMA(0, 1, At, B1); PG8_BAR; PG8_SCHED;
;             PG8_LDA(At, 0, 1); PG8_STAGE(PG8_SB(0, 0), b2, voffB); PG8_STAGE(PG8_SB(0, 1), b2 + hstepB, voffB); PG8_STAGE(PG8_SA(0, 0), a2, voffA);
.Lpka_da:
	s_waitcnt lgkmcnt(0)
	s_barrier
	s_setprio 1
	s_waitcnt lgkmcnt(0)
	v_mfma_f32_16x16x32_bf16 v[132:135], v[144:147], v[210:213], v[132:135]
	v_mfma_f32_16x16x32_bf16 v[128:131], v[152:155], v[210:213], v[128:131]
	v_mfma_f32_16x16x32_bf16 v[116:119], v[144:147], v[218:221], v[116:119]
	v_mfma_f32_16x16x32_bf16 v[112:115], v[152:155], v[218:221], v[112:115]
	v_mfma_f32_16x16x32_bf16 v[100:103], v[144:147], v[226:229], v[100:103]
	v_mfma_f32_16x16x32_bf16 v[96:99], v[152:155], v[226:229], v[96:99]
	v_mfma_f32_16x16x32_bf16 v[84:87], v[144:147], v[234:237], v[84:87]
	v_mfma_f32_16x16x32_bf16 v[80:83], v[152:155], v[234:237], v[80:83]
	v_mfma_f32_16x16x32_bf16 v[132:135], v[148:151], v[214:217], v[132:135]
	v_mfma_f32_16x16x32_bf16 v[128:131], v[156:159], v[214:217], v[128:131]
	v_mfma_f32_16x16x32_bf16 v[116:119], v[148:151], v[222:225], v[116:119]
	v_mfma_f32_16x16x32_bf16 v[112:115], v[156:159], v[222:225], v[112:115]
	v_mfma_f32_16x16x32_bf16 v[100:103], v[148:151], v[230:233], v[100:103]
	v_mfma_f32_16x16x32_bf16 v[96:99], v[156:159], v[230:233], v[96:99]
	v_mfma_f32_16x16x32_bf16 v[84:87], v[148:151], v[238:241], v[84:87]
	v_mfma_f32_16x16x32_bf16 v[80:83], v[156:159], v[238:241], v[80:83]
	s_setprio 0
	s_setprio 1
	v_mfma_f32_16x16x32_bf16 v[140:143], v[186:189], v[210:213], v[140:143]
	v_mfma_f32_16x16x32_bf16 v[136:139], v[202:205], v[210:213], v[136:139]
	v_mfma_f32_16x16x32_bf16 v[124:127], v[186:189], v[218:221], v[124:127]
	v_mfma_f32_16x16x32_bf16 v[120:123], v[202:205], v[218:221], v[120:123]
	v_mfma_f32_16x16x32_bf16 v[108:111], v[186:189], v[226:229], v[108:111]
	v_mfma_f32_16x16x32_bf16 v[104:107], v[202:205], v[226:229], v[104:107]
	v_mfma_f32_16x16x32_bf16 v[92:95], v[186:189], v[234:237], v[92:95]
	v_mfma_f32_16x16x32_bf16 v[88:91], v[202:205], v[234:237], v[88:91]
	v_mfma_f32_16x16x32_bf16 v[140:143], v[198:201], v[214:217], v[140:143]
	v_mfma_f32_16x16x32_bf16 v[136:139], v[206:209], v[214:217], v[136:139]
	v_mfma_f32_16x16x32_bf16 v[124:127], v[198:201], v[222:225], v[124:127]
	v_mfma_f32_16x16x32_bf16 v[120:123], v[206:209], v[222:225], v[120:123]
	v_mfma_f32_16x16x32_bf16 v[108:111], v[198:201], v[230:233], v[108:111]
	v_mfma_f32_16x16x32_bf16 v[104:107], v[206:209], v[230:233], v[104:107]
	v_mfma_f32_16x16x32_bf16 v[92:95], v[198:201], v[238:241], v[92:95]
	v_mfma_f32_16x16x32_bf16 v[88:91], v[206:209], v[238:241], v[88:91]
	s_setprio 0
	s_barrier
	s_add_i32 s82, s82, s15
	v_lshl_add_u64 v[242:243], s[72:73], 0, v[170:171]
	s_mov_b32 m0, s82
	ds_read_b128 v[210:213], v197 offset:16384
	ds_read_b128 v[214:217], v197 offset:17408
	ds_read_b128 v[218:221], v197 offset:18432
	ds_read_b128 v[222:225], v197 offset:19456
	ds_read_b128 v[226:229], v197 offset:20480
	ds_read_b128 v[230:233], v197 offset:21504
	ds_read_b128 v[234:237], v197 offset:22528
	ds_read_b128 v[238:241], v197 offset:23552
	global_load_lds_dwordx4 v[242:243], off
	s_add_i32 m0, s82, 0x2000
	s_add_u32 s82, s72, 0x10000
	v_lshl_add_u64 v[242:243], s[72:73], 0, v[166:167]
	s_addc_u32 s83, s73, 0
	s_add_i32 s86, s86, s15
	global_load_lds_dwordx4 v[242:243], off
	v_lshl_add_u64 v[242:243], s[82:83], 0, v[170:171]
	s_mov_b32 m0, s86
	global_load_lds_dwordx4 v[242:243], off
	v_lshl_add_u64 v[242:243], s[82:83], 0, v[166:167]
	s_add_i32 m0, s86, 0x2000
	s_nop 0
	global_load_lds_dwordx4 v[242:243], off
	v_lshl_add_u64 v[242:243], s[76:77], 0, v[172:173]
	s_mov_b32 m0, s63
	s_nop 0
	global_load_lds_dwordx4 v[242:243], off
	v_lshl_add_u64 v[242:243], s[76:77], 0, v[168:169]
	s_mov_b32 m0, s64
	s_nop 0
	global_load_lds_dwordx4 v[242:243], off
	s_lshl_b32 s100, s100, 1
	s_and_b32 s100, s100, 6
	s_bcnt1_i32_b32 vcc_lo, s100
	s_cmp_eq_u32 vcc_lo, 0
	s_cbranch_scc1 .Lpka_w8b
	s_cmp_eq_u32 vcc_lo, 1
	s_cbranch_scc1 .Lpka_w9b
	s_waitcnt vmcnt(10)
	s_branch .Lpka_db

; #define PG8_STAGE(bufoff, gbase, voff) do { _Pragma("unroll") for (int _i = 0; _i < 2; ++_i) \
;         __builtin_amdgcn_global_load_lds((const unsigned*)((const char*)(gbase) + (voff)[_i]), (PG8_LAS unsigned*)(lds + (bufoff) + ldsw + _i * 8192), 16, 0, 0); } while (0)
; #define PG8_LDA(dst, b, h) do { _Pragma("unroll") for (int m = 0; m < 4; ++m) _Pragma("unroll") for (int k = 0; k < 2; ++k) dst[m][k] = *(const PG8_LAS bf16x8*)(lds + PG8_SA(b, h) + aoff + m * 2048 + k * 1024); } while (0)
; #define PG8_LDB(dst, b, h) do { _Pragma("unroll") for (int n = 0; n < 2; ++n) _Pragma("unroll") for (int k = 0; k < 2; ++k) dst[n][k] = *(const PG8_LAS bf16x8*)(lds + PG8_SB(b, h) + boff + n * 2048 + k * 1024); } while (0)
; #define PG8_WAIT_V(n) asm volatile("s_waitcnt vmcnt(" #n ")" ::: "memory")
; #define PG8_WAIT_L(n) asm volatile("s_waitcnt lgkmcnt(" #n ")" ::: "memory")
; #define PG8_BAR __builtin_amdgcn_s_barrier()
; #define PG8_SCHED __builtin_amdgcn_sched_barrier(0)
;     ...
;             PG8_WAIT_V(8); PG8_WAIT_L(0); PG8_BAR; PG8_MMA(1, 0, At, B0); PG8_MMA(1, 1, At, B1); PG8_BAR; PG8_SCHED;
;             PG8_LDB(B0, 1, 0); PG8_LDB(B1, 1, 1); PG8_SCHED; PG8_LDA(At, 1, 0); PG8_STAGE(PG8_SA(0, 1), a2 + hstep, voffA);
.Lpka_db:
	s_waitcnt lgkmcnt(0)
	s_barrier
	s_setprio 1
	s_waitcnt lgkmcnt(0)
	v_mfma_f32_16x16x32_bf16 v[68:71], v[144:147], v[210:213], v[68:71]
	v_mfma_f32_16x16x32_bf16 v[64:67], v[152:155], v[210:213], v[64:67]
	v_mfma_f32_16x16x32_bf16 v[52:55], v[144:147], v[218:221], v[52:55]
	v_mfma_f32_16x16x32_bf16 v[48:51], v[152:155], v[218:221], v[48:51]
	v_mfma_f32_16x16x32_bf16 v[36:39], v[144:147], v[226:229], v[36:39]
	v_mfma_f32_16x16x32_bf16 v[32:35], v[152:155], v[226:229], v[32:35]
	v_mfma_f32_16x16x32_bf16 v[20:23], v[144:147], v[234:237], v[20:23]
	v_mfma_f32_16x16x32_bf16 v[16:19], v[152:155], v[234:237], v[16:19]
	v_mfma_f32_16x16x32_bf16 v[68:71], v[148:151], v[214:217], v[68:71]
	v_mfma_f32_16x16x32_bf16 v[64:67], v[156:159], v[214:217], v[64:67]
	v_mfma_f32_16x16x32_bf16 v[52:55], v[148:151], v[222:225], v[52:55]
	v_mfma_f32_16x16x32_bf16 v[48:51], v[156:159], v[222:225], v[48:51]
	v_mfma_f32_16x16x32_bf16 v[36:39], v[148:151], v[230:233], v[36:39]
	v_mfma_f32_16x16x32_bf16 v[32:35], v[156:159], v[230:233], v[32:35]
	v_mfma_f32_16x16x32_bf16 v[20:23], v[148:151], v[238:241], v[20:23]
	v_mfma_f32_16x16x32_bf16 v[16:19], v[156:159], v[238:241], v[16:19]
	s_setprio 0
	s_setprio 1
	v_mfma_f32_16x16x32_bf16 v[76:79], v[186:189], v[210:213], v[76:79]
	v_mfma_f32_16x16x32_bf16 v[72:75], v[202:205], v[210:213], v[72:75]
	v_mfma_f32_16x16x32_bf16 v[60:63], v[186:189], v[218:221], v[60:63]
	v_mfma_f32_16x16x32_bf16 v[56:59], v[202:205], v[218:221], v[56:59]
	v_mfma_f32_16x16x32_bf16 v[44:47], v[186:189], v[226:229], v[44:47]
	v_mfma_f32_16x16x32_bf16 v[40:43], v[202:205], v[226:229], v[40:43]
	v_mfma_f32_16x16x32_bf16 v[24:27], v[186:189], v[234:237], v[24:27]
	v_mfma_f32_16x16x32_bf16 v[28:31], v[202:205], v[234:237], v[28:31]
	v_mfma_f32_16x16x32_bf16 v[76:79], v[198:201], v[214:217], v[76:79]
	v_mfma_f32_16x16x32_bf16 v[72:75], v[206:209], v[214:217], v[72:75]
	v_mfma_f32_16x16x32_bf16 v[60:63], v[198:201], v[222:225], v[60:63]
	v_mfma_f32_16x16x32_bf16 v[56:59], v[206:209], v[222:225], v[56:59]
	v_mfma_f32_16x16x32_bf16 v[44:47], v[198:201], v[230:233], v[44:47]
	v_mfma_f32_16x16x32_bf16 v[40:43], v[206:209], v[230:233], v[40:43]
	v_mfma_f32_16x16x32_bf16 v[24:27], v[198:201], v[238:241], v[24:27]
	v_mfma_f32_16x16x32_bf16 v[28:31], v[206:209], v[238:241], v[28:31]
	s_setprio 0
	s_barrier
	s_add_i32 s82, 0, 0x18000
	s_add_i32 s83, 0, 0x1c000
	v_add_u32_e32 v156, s82, v195
	v_add_u32_e32 v183, s83, v195
	ds_read_b128 v[144:147], v156
	ds_read_b128 v[148:151], v156 offset:1024
	ds_read_b128 v[152:155], v156 offset:2048
	ds_read_b128 v[156:159], v156 offset:3072
	ds_read_b128 v[186:189], v183
	ds_read_b128 v[198:201], v183 offset:1024
	ds_read_b128 v[202:205], v183 offset:2048
	ds_read_b128 v[206:209], v183 offset:3072
	s_add_u32 s76, s76, 0x40000
	s_addc_u32 s77, s77, 0
	s_mov_b32 m0, s65
	v_lshl_add_u64 v[242:243], s[76:77], 0, v[172:173]
	ds_read_b128 v[210:213], v197 offset:32768
	ds_read_b128 v[214:217], v197 offset:33792
	ds_read_b128 v[218:221], v197 offset:34816
	ds_read_b128 v[222:225], v197 offset:35840
	ds_read_b128 v[226:229], v197 offset:36864
	ds_read_b128 v[230:233], v197 offset:37888
	ds_read_b128 v[234:237], v197 offset:38912
	ds_read_b128 v[238:241], v197 offset:39936
	global_load_lds_dwordx4 v[242:243], off
	v_lshl_add_u64 v[242:243], s[76:77], 0, v[168:169]
	s_mov_b32 m0, s66
	s_nop 0
	global_load_lds_dwordx4 v[242:243], off
	s_lshl_b32 s100, s100, 1
	s_and_b32 s100, s100, 6
	s_cmp_eq_u32 s101, 0
	s_cbranch_scc1 .Lpka_nc
	s_cmp_lt_i32 s81, 2
	s_cbranch_scc1 .Lpka_nc
	s_or_b32 s100, s100, 1
	s_cmp_eq_u32 s101, 8
	s_cbranch_scc1 .Lpka_s0c
	s_cmp_eq_u32 s101, 7
	s_cbranch_scc1 .Lpka_s1c
	s_cmp_eq_u32 s101, 6
	s_cbranch_scc1 .Lpka_s2c
	s_cmp_eq_u32 s101, 5
	s_cbranch_scc1 .Lpka_s3c
	s_cmp_eq_u32 s101, 4
	s_cbranch_scc1 .Lpka_s4c
	s_cmp_eq_u32 s101, 3
	s_cbranch_scc1 .Lpka_s5c
	s_cmp_eq_u32 s101, 2
	s_cbranch_scc1 .Lpka_s6c
	global_store_dwordx4 v[254:255], v[12:15], off offset:64
	s_branch .Lpka_ic

; #define PG8_STAGE(bufoff, gbase, voff) do { _Pragma("unroll") for (int _i = 0; _i < 2; ++_i) \
;         __builtin_amdgcn_global_load_lds((const unsigned*)((const char*)(gbase) + (voff)[_i]), (PG8_LAS unsigned*)(lds + (bufoff) + ldsw + _i * 8192), 16, 0, 0); } while (0)
; #define PG8_LDA(dst, b, h) do { _Pragma("unroll") for (int m = 0; m < 4; ++m) _Pragma("unroll") for (int k = 0; k < 2; ++k) dst[m][k] = *(const PG8_LAS bf16x8*)(lds + PG8_SA(b, h) + aoff + m * 2048 + k * 1024); } while (0)
; #define PG8_WAIT_V(n) asm volatile("s_waitcnt vmcnt(" #n ")" ::: "memory")
; #define PG8_WAIT_L(n) asm volatile("s_waitcnt lgkmcnt(" #n ")" ::: "memory")
; #define PG8_BAR __builtin_amdgcn_s_barrier()
; #define PG8_SCHED __builtin_amdgcn_sched_barrier(0)
;     ...
;             PG8_WAIT_V(8); PG8_WAIT_L(0); PG8_BAR; PG8_MMA(0, 0, At, B0); PG8_MMA(0, 1, At, B1); PG8_BAR; PG8_SCHED;
;             PG8_LDA(At, 1, 1); PG8_STAGE(PG8_SB(1, 0), b3, voffB); PG8_STAGE(PG8_SB(1, 1), b3 + hstepB, voffB); PG8_STAGE(PG8_SA(1, 0), a3, voffA);
.Lpka_dc:
	s_waitcnt lgkmcnt(0)
	s_barrier
	s_setprio 1
	s_waitcnt lgkmcnt(0)
	v_mfma_f32_16x16x32_bf16 v[132:135], v[144:147], v[210:213], v[132:135]
	v_mfma_f32_16x16x32_bf16 v[128:131], v[152:155], v[210:213], v[128:131]
	v_mfma_f32_16x16x32_bf16 v[116:119], v[144:147], v[218:221], v[116:119]
	v_mfma_f32_16x16x32_bf16 v[112:115], v[152:155], v[218:221], v[112:115]
	v_mfma_f32_16x16x32_bf16 v[100:103], v[144:147], v[226:229], v[100:103]
	v_mfma_f32_16x16x32_bf16 v[96:99], v[152:155], v[226:229], v[96:99]
	v_mfma_f32_16x16x32_bf16 v[84:87], v[144:147], v[234:237], v[84:87]
	v_mfma_f32_16x16x32_bf16 v[80:83], v[152:155], v[234:237], v[80:83]
	v_mfma_f32_16x16x32_bf16 v[132:135], v[148:151], v[214:217], v[132:135]
	v_mfma_f32_16x16x32_bf16 v[128:131], v[156:159], v[214:217], v[128:131]
	v_mfma_f32_16x16x32_bf16 v[116:119], v[148:151], v[222:225], v[116:119]
	v_mfma_f32_16x16x32_bf16 v[112:115], v[156:159], v[222:225], v[112:115]
	v_mfma_f32_16x16x32_bf16 v[100:103], v[148:151], v[230:233], v[100:103]
	v_mfma_f32_16x16x32_bf16 v[96:99], v[156:159], v[230:233], v[96:99]
	v_mfma_f32_16x16x32_bf16 v[84:87], v[148:151], v[238:241], v[84:87]
	v_mfma_f32_16x16x32_bf16 v[80:83], v[156:159], v[238:241], v[80:83]
	s_setprio 0
	s_setprio 1
	v_mfma_f32_16x16x32_bf16 v[140:143], v[186:189], v[210:213], v[140:143]
	v_mfma_f32_16x16x32_bf16 v[136:139], v[202:205], v[210:213], v[136:139]
	v_mfma_f32_16x16x32_bf16 v[124:127], v[186:189], v[218:221], v[124:127]
	v_mfma_f32_16x16x32_bf16 v[120:123], v[202:205], v[218:221], v[120:123]
	v_mfma_f32_16x16x32_bf16 v[108:111], v[186:189], v[226:229], v[108:111]
	v_mfma_f32_16x16x32_bf16 v[104:107], v[202:205], v[226:229], v[104:107]
	v_mfma_f32_16x16x32_bf16 v[92:95], v[186:189], v[234:237], v[92:95]
	v_mfma_f32_16x16x32_bf16 v[88:91], v[202:205], v[234:237], v[88:91]
	v_mfma_f32_16x16x32_bf16 v[140:143], v[198:201], v[214:217], v[140:143]
	v_mfma_f32_16x16x32_bf16 v[136:139], v[206:209], v[214:217], v[136:139]
	v_mfma_f32_16x16x32_bf16 v[124:127], v[198:201], v[222:225], v[124:127]
	v_mfma_f32_16x16x32_bf16 v[120:123], v[206:209], v[222:225], v[120:123]
	v_mfma_f32_16x16x32_bf16 v[108:111], v[198:201], v[230:233], v[108:111]
	v_mfma_f32_16x16x32_bf16 v[104:107], v[206:209], v[230:233], v[104:107]
	v_mfma_f32_16x16x32_bf16 v[92:95], v[198:201], v[238:241], v[92:95]
	v_mfma_f32_16x16x32_bf16 v[88:91], v[206:209], v[238:241], v[88:91]
	s_setprio 0
	s_barrier
	s_add_i32 vcc_lo, s82, s15
	v_lshl_add_u64 v[242:243], s[72:73], 0, v[170:171]
	v_lshl_add_u64 v[242:243], v[242:243], 0, s[4:5]
	s_mov_b32 m0, vcc_lo
	ds_read_b128 v[210:213], v197 offset:49152
	ds_read_b128 v[214:217], v197 offset:50176
	ds_read_b128 v[218:221], v197 offset:51200
	ds_read_b128 v[222:225], v197 offset:52224
	ds_read_b128 v[226:229], v197 offset:53248
	ds_read_b128 v[230:233], v197 offset:54272
	ds_read_b128 v[234:237], v197 offset:55296
	ds_read_b128 v[238:241], v197 offset:56320
	global_load_lds_dwordx4 v[242:243], off
	s_add_i32 m0, vcc_lo, 0x2000
	v_lshl_add_u64 v[242:243], s[72:73], 0, v[166:167]
	v_lshl_add_u64 v[242:243], v[242:243], 0, s[4:5]
	s_add_u32 s72, s72, 0x10080
	s_addc_u32 s73, s73, 0
	s_add_i32 vcc_lo, s83, s15
	global_load_lds_dwordx4 v[242:243], off
	v_lshl_add_u64 v[242:243], s[72:73], 0, v[170:171]
	s_mov_b32 m0, vcc_lo
	s_nop 0
	global_load_lds_dwordx4 v[242:243], off
	v_lshl_add_u64 v[242:243], s[72:73], 0, v[166:167]
	s_add_i32 m0, vcc_lo, 0x2000
	s_nop 0
	global_load_lds_dwordx4 v[242:243], off
	v_lshl_add_u64 v[242:243], s[76:77], 0, v[172:173]
	v_add_co_u32_e32 v242, vcc, 0xfffc0080, v242
	s_nop 1
	v_addc_co_u32_e32 v243, vcc, -1, v243, vcc
	s_mov_b32 m0, s74
	s_nop 0
	global_load_lds_dwordx4 v[242:243], off
	v_lshl_add_u64 v[242:243], s[76:77], 0, v[168:169]
	v_add_co_u32_e32 v242, vcc, 0xfffc0080, v242
	s_nop 1
	v_addc_co_u32_e32 v243, vcc, -1, v243, vcc
	s_mov_b32 m0, s75
	s_nop 0
	global_load_lds_dwordx4 v[242:243], off
	s_lshl_b32 s100, s100, 1
	s_and_b32 s100, s100, 6
	s_bcnt1_i32_b32 vcc_lo, s100
	s_cmp_eq_u32 vcc_lo, 0
	s_cbranch_scc1 .Lpka_w8e
	s_cmp_eq_u32 vcc_lo, 1
	s_cbranch_scc1 .Lpka_w9e
	s_waitcnt vmcnt(10)
	s_branch .Lpka_de

; __device__ __forceinline__ float sum_x16(float v) { float a, b; swap16(v, a, b); return a + b; }
; __device__ __forceinline__ float sum_x32(float v) { float a, b; swap32(v, a, b); return a + b; }
; __device__ __forceinline__ void st16_wt(void* p, u32x4 v) { if (WT_STORES) asm volatile("global_store_dwordx4 %0, %1, off sc1\n\ts_nop 1" :: "v"(p), "v"(v) : "memory"); else *(u32x4*)p = v; }
; __device__ __forceinline__ unsigned cvt_pk_bf16(float lo, float hi) { unsigned r; asm volatile("v_cvt_pk_bf16_f32 %0, %1, %2" : "=v"(r) : "v"(lo), "v"(hi)); return r; }
;     __device__ __forceinline__ void operator()(const f32x4 (&acc)[2][2][4][2], const Unit& u, int wr, int wc, int fr, int fq, const bool reuse, PG8_LAS float* rscr, PG8_LAS const float* gains) const {
;     ...
; #pragma unroll
;         for (int ai = 0; ai < 2; ++ai)
; #pragma unroll
;             for (int m = 0; m < 4; ++m) {
;                 const int r = u.pm * BM + ai * HALF + wr * 64 + m * 16 + fr;
;                 const float rsv = (MODE == 0) ? 1.0f : rsvv[ai][m];
;                 f32x4 v[2][2];
; #pragma unroll
;                 for (int bj = 0; bj < 2; ++bj)
; #pragma unroll
;                     for (int n = 0; n < 2; ++n) v[bj][n] = acc[ai][bj][m][n] * rsv;
;                 if (type < 2) {
;                     float ss = 0.f;
; #pragma unroll
;                     for (int bj = 0; bj < 2; ++bj)
; #pragma unroll
;                         for (int n = 0; n < 2; ++n) { const f32x4 x = v[bj][n]; ss += (x[0] * x[0] + x[1] * x[1]) + (x[2] * x[2] + x[3] * x[3]); }
;                     ss = sum_x16(ss); ss = sum_x32(ss);
;                     const float inv = __builtin_amdgcn_rsqf(ss * (1.0f / 64.0f) + RMS_EPS);
; #pragma unroll
;                     for (int bj = 0; bj < 2; ++bj)
; #pragma unroll
;                         for (int n = 0; n < 2; ++n) v[bj][n] = v[bj][n] * gv[bj][n] * inv;
;                 }
;                 bf16_t* p = p0 + (size_t)(8 * ai + m) * step16;
; #pragma unroll
;                 for (int bj = 0; bj < 2; ++bj) { u32x4 w; w.x = cvt_pk_bf16(v[bj][0][0], v[bj][0][1]); w.y = cvt_pk_bf16(v[bj][0][2], v[bj][0][3]); w.z = cvt_pk_bf16(v[bj][1][0], v[bj][1][1]); w.w = cvt_pk_bf16(v[bj][1][2], v[bj][1][3]);
;                     st16_wt(p + 32 * bj, w); }
.LBB0_240:
	s_nop 0
	v_mad_u64_u32 v[80:81], s[12:13], s72, 10, v[96:97]
	v_mov_b32_e32 v254, v80
	v_mov_b32_e32 v255, v81
	s_and_b64 vcc, exec, s[38:39]
	v_cvt_pk_bf16_f32 v68, v68, v69
	v_cvt_pk_bf16_f32 v69, v70, v71
	v_cvt_pk_bf16_f32 v70, v64, v65
	v_cvt_pk_bf16_f32 v71, v66, v67
	v_mov_b32_e32 v244, v68
	v_mov_b32_e32 v245, v69
	v_mov_b32_e32 v246, v70
	v_mov_b32_e32 v247, v71
	v_cvt_pk_bf16_f32 v64, v76, v77
	v_cvt_pk_bf16_f32 v65, v78, v79
	v_cvt_pk_bf16_f32 v66, v72, v73
	v_cvt_pk_bf16_f32 v67, v74, v75
	v_mov_b32_e32 v248, v64
	v_mov_b32_e32 v249, v65
	v_mov_b32_e32 v250, v66
	v_mov_b32_e32 v251, v67
	s_cbranch_vccnz .LBB0_242
	s_nop 0
	v_mul_f32_e32 v64, v53, v53
	v_mul_f32_e32 v65, v55, v55
	v_fmac_f32_e32 v64, v52, v52
	v_fmac_f32_e32 v65, v54, v54
	v_add_f32_e32 v64, v64, v65
	v_mul_f32_e32 v65, v49, v49
	v_mul_f32_e32 v66, v51, v51
	v_fmac_f32_e32 v65, v48, v48
	v_fmac_f32_e32 v66, v50, v50
	v_add_f32_e32 v65, v65, v66
	v_add_f32_e32 v64, v64, v65
	v_mul_f32_e32 v65, v61, v61
	v_mul_f32_e32 v66, v63, v63
	v_fmac_f32_e32 v65, v60, v60
	v_fmac_f32_e32 v66, v62, v62
	v_add_f32_e32 v65, v65, v66
	v_add_f32_e32 v64, v64, v65
	v_mul_f32_e32 v65, v57, v57
	v_mul_f32_e32 v66, v59, v59
	v_fmac_f32_e32 v65, v56, v56
	v_fmac_f32_e32 v66, v58, v58
	v_add_f32_e32 v65, v65, v66
	v_add_f32_e32 v64, v64, v65
	v_mov_b32_e32 v65, v64
	s_nop 1
	v_permlane16_swap_b32_e32 v64, v65
	v_add_f32_e32 v64, v64, v65
	v_mov_b32_e32 v65, v64
	s_nop 1
	v_permlane32_swap_b32_e32 v64, v65
	v_add_f32_e32 v64, v64, v65
	v_fmamk_f32 v64, v64, 0x3c800000, v190
	v_rsq_f32_e32 v64, v64
	s_waitcnt lgkmcnt(0)
	v_pk_mul_f32 v[54:55], v[54:55], v[158:159]
	v_pk_mul_f32 v[52:53], v[52:53], v[156:157]
	v_pk_mul_f32 v[50:51], v[50:51], v[154:155]
	v_pk_mul_f32 v[48:49], v[48:49], v[152:153]
	v_pk_mul_f32 v[62:63], v[62:63], v[150:151]
	v_pk_mul_f32 v[60:61], v[60:61], v[148:149]
	v_pk_mul_f32 v[58:59], v[58:59], v[146:147]
	v_pk_mul_f32 v[56:57], v[56:57], v[144:145]
	v_pk_mul_f32 v[54:55], v[54:55], v[64:65] op_sel_hi:[1,0]
	v_pk_mul_f32 v[52:53], v[52:53], v[64:65] op_sel_hi:[1,0]
	v_pk_mul_f32 v[50:51], v[50:51], v[64:65] op_sel_hi:[1,0]
	v_pk_mul_f32 v[48:49], v[48:49], v[64:65] op_sel_hi:[1,0]
	v_pk_mul_f32 v[62:63], v[62:63], v[64:65] op_sel_hi:[1,0]
	v_pk_mul_f32 v[60:61], v[60:61], v[64:65] op_sel_hi:[1,0]
	v_pk_mul_f32 v[58:59], v[58:59], v[64:65] op_sel_hi:[1,0]
	v_pk_mul_f32 v[56:57], v[56:57], v[64:65] op_sel_hi:[1,0]
.LBB0_242:
	s_nop 0
	v_lshl_add_u64 v[64:65], v[80:81], 0, s[88:89]
	s_and_b64 vcc, exec, s[38:39]
	v_cvt_pk_bf16_f32 v52, v52, v53
	v_cvt_pk_bf16_f32 v53, v54, v55
	v_cvt_pk_bf16_f32 v54, v48, v49
	v_cvt_pk_bf16_f32 v55, v50, v51
	v_mov_b32_e32 v214, v52
	v_mov_b32_e32 v215, v53
	v_mov_b32_e32 v216, v54
	v_mov_b32_e32 v217, v55
	v_cvt_pk_bf16_f32 v48, v60, v61
	v_cvt_pk_bf16_f32 v49, v62, v63
	v_cvt_pk_bf16_f32 v50, v56, v57
	v_cvt_pk_bf16_f32 v51, v58, v59
	v_mov_b32_e32 v218, v48
	v_mov_b32_e32 v219, v49
	v_mov_b32_e32 v220, v50
	v_mov_b32_e32 v221, v51
	s_cbranch_vccnz .LBB0_244
	s_nop 0
	v_mul_f32_e32 v48, v37, v37
	v_mul_f32_e32 v49, v39, v39
	v_fmac_f32_e32 v48, v36, v36
	v_fmac_f32_e32 v49, v38, v38
	v_add_f32_e32 v48, v48, v49
	v_mul_f32_e32 v49, v33, v33
	v_mul_f32_e32 v50, v35, v35
	v_fmac_f32_e32 v49, v32, v32
	v_fmac_f32_e32 v50, v34, v34
	v_add_f32_e32 v49, v49, v50
	v_add_f32_e32 v48, v48, v49
	v_mul_f32_e32 v49, v45, v45
	v_mul_f32_e32 v50, v47, v47
	v_fmac_f32_e32 v49, v44, v44
	v_fmac_f32_e32 v50, v46, v46
	v_add_f32_e32 v49, v49, v50
	v_add_f32_e32 v48, v48, v49
	v_mul_f32_e32 v49, v41, v41
	v_mul_f32_e32 v50, v43, v43
	v_fmac_f32_e32 v49, v40, v40
	v_fmac_f32_e32 v50, v42, v42
	v_add_f32_e32 v49, v49, v50
	v_add_f32_e32 v48, v48, v49
	v_mov_b32_e32 v49, v48
	s_nop 1
	v_permlane16_swap_b32_e32 v48, v49
	v_add_f32_e32 v48, v48, v49
	v_mov_b32_e32 v49, v48
	s_nop 1
	v_permlane32_swap_b32_e32 v48, v49
	v_add_f32_e32 v48, v48, v49
	v_fmamk_f32 v48, v48, 0x3c800000, v190
	v_rsq_f32_e32 v48, v48
	s_waitcnt lgkmcnt(0)
	v_pk_mul_f32 v[38:39], v[38:39], v[158:159]
	v_pk_mul_f32 v[36:37], v[36:37], v[156:157]
	v_pk_mul_f32 v[34:35], v[34:35], v[154:155]
	v_pk_mul_f32 v[32:33], v[32:33], v[152:153]
	v_pk_mul_f32 v[46:47], v[46:47], v[150:151]
	v_pk_mul_f32 v[44:45], v[44:45], v[148:149]
	v_pk_mul_f32 v[42:43], v[42:43], v[146:147]
	v_pk_mul_f32 v[40:41], v[40:41], v[144:145]
	v_pk_mul_f32 v[38:39], v[38:39], v[48:49] op_sel_hi:[1,0]
	v_pk_mul_f32 v[36:37], v[36:37], v[48:49] op_sel_hi:[1,0]
	v_pk_mul_f32 v[34:35], v[34:35], v[48:49] op_sel_hi:[1,0]
	v_pk_mul_f32 v[32:33], v[32:33], v[48:49] op_sel_hi:[1,0]
	v_pk_mul_f32 v[46:47], v[46:47], v[48:49] op_sel_hi:[1,0]
	v_pk_mul_f32 v[44:45], v[44:45], v[48:49] op_sel_hi:[1,0]
	v_pk_mul_f32 v[42:43], v[42:43], v[48:49] op_sel_hi:[1,0]
	v_pk_mul_f32 v[40:41], v[40:41], v[48:49] op_sel_hi:[1,0]

; __device__ __forceinline__ float wave_sum(float v) { v += dpp_mov<0xB1>(v); v += dpp_mov<0x4E>(v); v += dpp_mov<0x141>(v); v += dpp_mov<0x140>(v); v = sum_x16(v); return sum_x32(v); }
; __device__ __forceinline__ void st16_wt(void* p, u32x4 v) { if (WT_STORES) asm volatile("global_store_dwordx4 %0, %1, off sc1\n\ts_nop 1" :: "v"(p), "v"(v) : "memory"); else *(u32x4*)p = v; }
;     __device__ __forceinline__ void side_finish(const Side& s, int lane) const {
;         if (MODE == 0 && s.row < xrows) {
;             float q = 0.f;
; #pragma unroll
;             for (int j = 0; j < 4; ++j) q += (s.v[j][0] * s.v[j][0] + s.v[j][1] * s.v[j][1]) + (s.v[j][2] * s.v[j][2] + s.v[j][3] * s.v[j][3]);
;             const float rstd = __builtin_amdgcn_rsqf(wave_sum(q) * (1.0f / 1024.0f) + 1e-6f);
;             const bool odd = lane & 1;
;             bf16_t* orow = xd + (size_t)s.row * 1024 + 4 * (lane & ~1);
; #pragma unroll
;             for (int jp = 0; jp < 2; ++jp) {
;                 const int ja = 2 * jp, jb = 2 * jp + 1;
;                 const unsigned pax = cvt_pk_bf16(s.v[ja][0] * rstd, s.v[ja][1] * rstd), pay = cvt_pk_bf16(s.v[ja][2] * rstd, s.v[ja][3] * rstd);
;                 const unsigned pbx = cvt_pk_bf16(s.v[jb][0] * rstd, s.v[jb][1] * rstd), pby = cvt_pk_bf16(s.v[jb][2] * rstd, s.v[jb][3] * rstd);
;                 const unsigned rx = (unsigned)__builtin_amdgcn_update_dpp(0, (int)(odd ? pax : pbx), 0xB1, 0xF, 0xF, true), ry = (unsigned)__builtin_amdgcn_update_dpp(0, (int)(odd ? pay : pby), 0xB1, 0xF, 0xF, true);
;                 u32x4 w; w.x = odd ? rx : pax; w.y = odd ? ry : pay; w.z = odd ? pbx : rx; w.w = odd ? pby : ry;
;                 *(u32x4*)(orow + (odd ? 256 * jb : 256 * ja)) = w;
;             }
;     __device__ __forceinline__ void operator()(const f32x4 (&acc)[2][2][4][2], const Unit& u, int wr, int wc, int fr, int fq, const bool reuse, PG8_LAS float* rscr, PG8_LAS const float* gains) const {
;     ...
;                 bf16_t* p = p0 + (size_t)(8 * ai + m) * step16;
; #pragma unroll
;                 for (int bj = 0; bj < 2; ++bj) { u32x4 w; w.x = cvt_pk_bf16(v[bj][0][0], v[bj][0][1]); w.y = cvt_pk_bf16(v[bj][0][2], v[bj][0][3]); w.z = cvt_pk_bf16(v[bj][1][0], v[bj][1][1]); w.w = cvt_pk_bf16(v[bj][1][2], v[bj][1][3]);
;                     st16_wt(p + 32 * bj, w); }
.LBB0_246:
	s_nop 0
	v_lshl_add_u64 v[32:33], v[48:49], 0, s[88:89]
	s_andn2_b64 vcc, exec, s[80:81]
	v_cvt_pk_bf16_f32 v20, v20, v21
	v_cvt_pk_bf16_f32 v21, v22, v23
	v_cvt_pk_bf16_f32 v22, v16, v17
	v_cvt_pk_bf16_f32 v23, v18, v19
	v_mov_b32_e32 v8, v20
	v_mov_b32_e32 v9, v21
	v_mov_b32_e32 v10, v22
	v_mov_b32_e32 v11, v23
	v_cvt_pk_bf16_f32 v16, v24, v25
	v_cvt_pk_bf16_f32 v17, v26, v27
	v_cvt_pk_bf16_f32 v18, v28, v29
	v_cvt_pk_bf16_f32 v19, v30, v31
	v_mov_b32_e32 v12, v16
	v_mov_b32_e32 v13, v17
	v_mov_b32_e32 v14, v18
	v_mov_b32_e32 v15, v19
	s_mov_b32 s101, 8
	s_cbranch_vccnz .LBB0_248
	s_waitcnt vmcnt(8)
	v_mul_f32_e32 v16, v211, v211
	v_mul_f32_e32 v17, v213, v213
	v_fmac_f32_e32 v16, v210, v210
	v_fmac_f32_e32 v17, v212, v212
	v_add_f32_e32 v16, v16, v17
	v_mul_f32_e32 v17, v207, v207
	v_mul_f32_e32 v18, v209, v209
	v_fmac_f32_e32 v17, v206, v206
	v_fmac_f32_e32 v18, v208, v208
	v_add_f32_e32 v17, v17, v18
	v_add_f32_e32 v16, v17, v16
	v_mul_f32_e32 v17, v203, v203
	v_mul_f32_e32 v18, v205, v205
	v_fmac_f32_e32 v17, v202, v202
	v_fmac_f32_e32 v18, v204, v204
	v_add_f32_e32 v17, v17, v18
	v_add_f32_e32 v16, v17, v16
	v_mul_f32_e32 v17, v199, v199
	v_mul_f32_e32 v18, v201, v201
	v_fmac_f32_e32 v17, v198, v198
	v_fmac_f32_e32 v18, v200, v200
	v_add_f32_e32 v17, v17, v18
	v_add_f32_e32 v16, v17, v16
	s_ashr_i32 s77, s76, 31
	s_lshl_b64 s[12:13], s[76:77], 11
	v_add_f32_dpp v16, v16, v16 quad_perm:[1,0,3,2] row_mask:0xf bank_mask:0xf bound_ctrl:1
	v_lshl_add_u64 v[20:21], v[176:177], 0, s[12:13]
	v_mov_b32_e32 v183, v161
	v_add_f32_dpp v16, v16, v16 quad_perm:[2,3,0,1] row_mask:0xf bank_mask:0xf bound_ctrl:1
	v_mov_b32_e32 v185, v161
	s_nop 0
	v_add_f32_dpp v16, v16, v16 row_half_mirror row_mask:0xf bank_mask:0xf bound_ctrl:1
	s_nop 1
	v_add_f32_dpp v16, v16, v16 row_mirror row_mask:0xf bank_mask:0xf bound_ctrl:1
	v_mov_b32_e32 v17, v16
	s_nop 1
	v_permlane16_swap_b32_e32 v16, v17
	v_add_f32_e32 v16, v16, v17
	v_mov_b32_e32 v17, v16
	s_nop 1
	v_permlane32_swap_b32_e32 v16, v17
	v_add_f32_e32 v16, v16, v17
	v_fmamk_f32 v16, v16, 0x3a800000, v190
	v_rsq_f32_e32 v24, v16
	s_nop 0
	v_mul_f32_e32 v16, v210, v24
	v_mul_f32_e32 v17, v211, v24
	v_cvt_pk_bf16_f32 v16, v16, v17
	v_mul_f32_e32 v17, v212, v24
	v_mul_f32_e32 v18, v213, v24
	v_cvt_pk_bf16_f32 v17, v17, v18
	v_mul_f32_e32 v18, v206, v24
	v_mul_f32_e32 v19, v207, v24
	v_cvt_pk_bf16_f32 v18, v18, v19
	v_mul_f32_e32 v19, v208, v24
	v_mul_f32_e32 v22, v209, v24
	v_cvt_pk_bf16_f32 v19, v19, v22
	v_cndmask_b32_e64 v22, v16, v18, s[34:35]
	v_cndmask_b32_e64 v23, v17, v19, s[34:35]
	s_nop 0
	v_mov_b32_dpp v22, v22 quad_perm:[1,0,3,2] row_mask:0xf bank_mask:0xf bound_ctrl:1
	v_mov_b32_dpp v23, v23 quad_perm:[1,0,3,2] row_mask:0xf bank_mask:0xf bound_ctrl:1
	v_cndmask_b32_e64 v16, v22, v16, s[34:35]
	v_cndmask_b32_e64 v17, v23, v17, s[34:35]
	v_cndmask_b32_e64 v18, v18, v22, s[34:35]
	v_cndmask_b32_e64 v19, v19, v23, s[34:35]
	v_lshl_add_u64 v[22:23], v[20:21], 0, v[182:183]
	global_store_dwordx4 v[22:23], v[16:19], off
	v_mul_f32_e32 v22, v201, v24
	v_lshl_add_u64 v[20:21], v[20:21], 0, v[184:185]
	v_mul_f32_e32 v16, v202, v24
	v_mul_f32_e32 v17, v203, v24
	v_cvt_pk_bf16_f32 v16, v16, v17
	v_mul_f32_e32 v17, v204, v24
	v_mul_f32_e32 v18, v205, v24
	v_cvt_pk_bf16_f32 v17, v17, v18
	v_mul_f32_e32 v18, v198, v24
	v_mul_f32_e32 v19, v199, v24
	v_cvt_pk_bf16_f32 v18, v18, v19
	v_mul_f32_e32 v19, v200, v24
	v_cvt_pk_bf16_f32 v19, v19, v22
	v_cndmask_b32_e64 v22, v16, v18, s[34:35]
	v_cndmask_b32_e64 v23, v17, v19, s[34:35]
	s_nop 0
	v_mov_b32_dpp v22, v22 quad_perm:[1,0,3,2] row_mask:0xf bank_mask:0xf bound_ctrl:1
	v_mov_b32_dpp v23, v23 quad_perm:[1,0,3,2] row_mask:0xf bank_mask:0xf bound_ctrl:1
	v_cndmask_b32_e64 v16, v22, v16, s[34:35]
	v_cndmask_b32_e64 v17, v23, v17, s[34:35]
	v_cndmask_b32_e64 v18, v18, v22, s[34:35]
	v_cndmask_b32_e64 v19, v19, v23, s[34:35]
	global_store_dwordx4 v[20:21], v[16:19], off

; __device__ __forceinline__ void st16_wt(void* p, u32x4 v) { if (WT_STORES) asm volatile("global_store_dwordx4 %0, %1, off sc1\n\ts_nop 1" :: "v"(p), "v"(v) : "memory"); else *(u32x4*)p = v; }
; __device__ __forceinline__ unsigned cvt_pk_bf16(float lo, float hi) { unsigned r; asm volatile("v_cvt_pk_bf16_f32 %0, %1, %2" : "=v"(r) : "v"(lo), "v"(hi)); return r; }
;     __device__ __forceinline__ void operator()(const f32x4 (&acc)[2][2][4][2], const Unit& u, int wr, int wc, int fr, int fq, const bool reuse, PG8_LAS float* rscr, PG8_LAS const float* gains) const {
;     ...
;                 bf16_t* p = p0 + (size_t)(8 * ai + m) * step16;
; #pragma unroll
;                 for (int bj = 0; bj < 2; ++bj) { u32x4 w; w.x = cvt_pk_bf16(v[bj][0][0], v[bj][0][1]); w.y = cvt_pk_bf16(v[bj][0][2], v[bj][0][3]); w.z = cvt_pk_bf16(v[bj][1][0], v[bj][1][1]); w.w = cvt_pk_bf16(v[bj][1][2], v[bj][1][3]);
;                     st16_wt(p + 32 * bj, w); }
.LBB0_253:
	s_cmp_eq_u32 s101, 0
	s_cbranch_scc1 .Lpka_fd
	global_store_dwordx4 v[254:255], v[244:247], off
	global_store_dwordx4 v[254:255], v[248:251], off offset:64
	v_add_co_u32_e32 v254, vcc, s88, v254
	s_nop 1
	v_addc_co_u32_e32 v255, vcc, 0, v255, vcc
	global_store_dwordx4 v[254:255], v[214:217], off
	global_store_dwordx4 v[254:255], v[218:221], off offset:64
	v_add_co_u32_e32 v254, vcc, s88, v254
	s_nop 1
	v_addc_co_u32_e32 v255, vcc, 0, v255, vcc
	global_store_dwordx4 v[254:255], v[0:3], off
	global_store_dwordx4 v[254:255], v[4:7], off offset:64
	v_add_co_u32_e32 v254, vcc, s88, v254
	s_nop 1
	v_addc_co_u32_e32 v255, vcc, 0, v255, vcc
	global_store_dwordx4 v[254:255], v[8:11], off
	global_store_dwordx4 v[254:255], v[12:15], off offset:64
	s_mov_b32 s101, 0
